# LN2 row statistics: ds_bpermute all-reduce chains -> DPP (same butterfly order), on top of static-first attention units
# speedup vs baseline: 1.0008x; 1.0008x over previous
; DI unsigned pk2(float lo, float hi) { f32x2 v = {lo, hi}; bf16x2v b = __builtin_convertvector(v, bf16x2v); return __builtin_bit_cast(unsigned, b); }
; DI float frsq(float x) { return __builtin_amdgcn_rsqf(x); }
; DI void phase_ln2(KArgs args, LAS unsigned char* L, const Ctx& c) {
;     ...
;         float s = 0.f;
; #pragma unroll
;         for (int j = 0; j < 4; ++j) s += (v[j][0] + v[j][1]) + (v[j][2] + v[j][3]);
;         const float mean = wave_sum(s) * (1.0f / D); float s2 = 0.f;
; #pragma unroll
;         for (int j = 0; j < 4; ++j) { v[j] = v[j] - mean; s2 += (v[j][0] * v[j][0] + v[j][1] * v[j][1]) + (v[j][2] * v[j][2] + v[j][3] * v[j][3]); }
;         const float rstd = frsq(wave_sum(s2) * (1.0f / D) + LN_EPS);
; #pragma unroll
;         for (int j = 0; j < 4; ++j) { v[j] = v[j] * rstd * gv[j] + bv[j];
;             if (!c.dry) {
;                 if (l == 1) *(f32x4*)(xr + 4 * lane + 256 * j) = v[j];
;                 else { u32x2 w; w.x = pk2(v[j][0], v[j][1]); w.y = pk2(v[j][2], v[j][3]); *(u32x2*)(XB + tok * D + 4 * lane + 256 * j) = w;
;                     *(unsigned*)(WSP(unsigned char, WS_XB8) + tok * D + 4 * lane + 256 * j) = pk4_fp8(v[j][0], v[j][1], v[j][2], v[j][3]); } } }
.LBB0_1675:
	v_mov_b32_e32 v70, v39
	v_mov_b32_e32 v71, v36
	v_mov_b32_e32 v72, v38
	v_mov_b32_e32 v73, v37
	v_pk_add_f32 v[70:71], v[70:71], v[72:73]
	v_mov_b32_e32 v72, v69
	v_mov_b32_e32 v73, v66
	v_mov_b32_e32 v74, v68
	v_mov_b32_e32 v75, v67
	v_pk_add_f32 v[72:73], v[72:73], v[74:75]
	v_add_f32_e32 v70, v70, v71
	v_pk_add_f32 v[72:73], v[72:73], v[72:73] op_sel_hi:[0,1]
	v_add_f32_e32 v71, 0, v70
	v_add_f32_e32 v75, v64, v65
	v_add_f32_e32 v83, v62, v63
	v_mov_b32_e32 v74, v60
	v_mov_b32_e32 v82, v61
	v_mov_b32_e32 v72, v58
	v_mov_b32_e32 v70, v59
	v_pk_add_f32 v[74:75], v[74:75], v[82:83]
	v_pk_add_f32 v[70:71], v[72:73], v[70:71]
	s_ashr_i32 s1, s0, 31
	v_pk_add_f32 v[70:71], v[74:75], v[70:71]
	v_readlane_b32 s14, v254, 10
	v_add_f32_e32 v70, v70, v71
	s_lshl_b64 s[4:5], s[0:1], 11
	v_readlane_b32 s15, v254, 11
	s_lshl_b64 s[8:9], s[0:1], 10
	s_and_b64 vcc, exec, s[14:15]
	s_nop 1
	v_add_f32_dpp v70, v70, v70 quad_perm:[1,0,3,2] row_mask:0xf bank_mask:0xf
	s_nop 1
	v_add_f32_dpp v70, v70, v70 quad_perm:[2,3,0,1] row_mask:0xf bank_mask:0xf
	s_nop 1
	v_add_f32_dpp v70, v70, v70 row_half_mirror row_mask:0xf bank_mask:0xf
	s_nop 1
	v_add_f32_dpp v70, v70, v70 row_mirror row_mask:0xf bank_mask:0xf
	s_nop 1
	v_add_f32_dpp v70, v70, v70 row_bcast:15 row_mask:0xa bank_mask:0xf
	s_nop 1
	v_add_f32_dpp v70, v70, v70 row_bcast:31 row_mask:0xc bank_mask:0xf
	s_nop 1
	v_readlane_b32 s16, v70, 63
	s_nop 1
	v_mov_b32_e32 v84, s16
	v_fmac_f32_e32 v39, 0xba800000, v84
	v_fmac_f32_e32 v38, 0xba800000, v84
	v_fmac_f32_e32 v37, 0xba800000, v84
	v_fmac_f32_e32 v36, 0xba800000, v84
	v_pk_mul_f32 v[70:71], v[36:37], v[36:37]
	v_pk_mul_f32 v[72:73], v[38:39], v[38:39]
	v_fmac_f32_e32 v67, 0xba800000, v84
	v_pk_mov_b32 v[74:75], v[72:73], v[70:71] op_sel:[1,0]
	v_mov_b32_e32 v73, v71
	v_fmac_f32_e32 v66, 0xba800000, v84
	v_fmac_f32_e32 v69, 0xba800000, v84
	v_pk_add_f32 v[70:71], v[74:75], v[72:73]
	v_fmac_f32_e32 v68, 0xba800000, v84
	v_pk_add_f32 v[70:71], v[70:71], v[70:71] op_sel_hi:[0,1]
	v_pk_mul_f32 v[72:73], v[66:67], v[66:67]
	v_pk_mul_f32 v[74:75], v[68:69], v[68:69]
	v_fmac_f32_e32 v64, 0xba800000, v84
	v_pk_mov_b32 v[82:83], v[74:75], v[72:73] op_sel:[1,0]
	v_mov_b32_e32 v75, v73
	v_fmac_f32_e32 v62, 0xba800000, v84
	v_fmac_f32_e32 v65, 0xba800000, v84
	v_mul_f32_e32 v70, v64, v64
	v_pk_add_f32 v[72:73], v[82:83], v[74:75]
	v_fmac_f32_e32 v63, 0xba800000, v84
	v_pk_fma_f32 v[74:75], v[64:65], v[64:65], v[70:71] op_sel_hi:[1,1,0]
	v_mul_f32_e32 v70, v62, v62
	v_pk_add_f32 v[72:73], v[72:73], v[72:73] op_sel_hi:[0,1]
	v_pk_fma_f32 v[82:83], v[62:63], v[62:63], v[70:71] op_sel_hi:[1,1,0]
	v_fmac_f32_e32 v59, 0xba800000, v84
	v_fmac_f32_e32 v58, 0xba800000, v84
	v_fmac_f32_e32 v61, 0xba800000, v84
	v_fmac_f32_e32 v60, 0xba800000, v84
	v_mul_f32_e32 v74, v60, v60
	v_mul_f32_e32 v82, v61, v61
	v_mul_f32_e32 v70, v58, v58
	v_mul_f32_e32 v72, v59, v59
	v_pk_add_f32 v[74:75], v[74:75], v[82:83]
	v_pk_add_f32 v[70:71], v[70:71], v[72:73]
	s_nop 0
	v_pk_add_f32 v[70:71], v[74:75], v[70:71]
	s_nop 0
	v_add_f32_e32 v70, v70, v71
	s_nop 1
	v_add_f32_dpp v70, v70, v70 quad_perm:[1,0,3,2] row_mask:0xf bank_mask:0xf
	s_nop 1
	v_add_f32_dpp v70, v70, v70 quad_perm:[2,3,0,1] row_mask:0xf bank_mask:0xf
	s_nop 1
	v_add_f32_dpp v70, v70, v70 row_half_mirror row_mask:0xf bank_mask:0xf
	s_nop 1
	v_add_f32_dpp v70, v70, v70 row_mirror row_mask:0xf bank_mask:0xf
	s_nop 1
	v_add_f32_dpp v70, v70, v70 row_bcast:15 row_mask:0xa bank_mask:0xf
	s_nop 1
	v_add_f32_dpp v70, v70, v70 row_bcast:31 row_mask:0xc bank_mask:0xf
	s_nop 1
	v_readlane_b32 s16, v70, 63
	s_nop 1
	v_mov_b32_e32 v70, s16
	v_fmamk_f32 v70, v70, 0x3a800000, v214
	v_rsq_f32_e32 v74, v70
	v_lshl_add_u64 v[70:71], v[42:43], 0, s[4:5]
	s_mov_b64 s[4:5], -1
	v_pk_mul_f32 v[72:73], v[38:39], v[74:75] op_sel_hi:[1,0]
	v_pk_mul_f32 v[36:37], v[36:37], v[74:75] op_sel_hi:[1,0]
	s_nop 0
	v_pk_fma_f32 v[38:39], v[6:7], v[36:37], v[10:11]
	v_pk_fma_f32 v[36:37], v[4:5], v[72:73], v[8:9]
	s_cbranch_vccz .LBB0_1677
	v_mov_b32_e32 v75, v3
	v_cvt_pk_fp8_f32 v75, v36, v37
	v_cvt_pk_bf16_f32 v72, v36, v37
	v_cvt_pk_bf16_f32 v73, v38, v39
	global_store_dwordx2 v[70:71], v[72:73], off
	v_cvt_pk_fp8_f32 v75, v38, v39 op_sel:[0,0,1]
	v_lshl_add_u64 v[72:73], v[48:49], 0, s[8:9]
	s_mov_b64 s[4:5], 0
	global_store_dword v[72:73], v75, off
